# v2 + HGRN2 chain: exact counted vmcnt at prefetch hand-offs (no longer forces acknowledgement of the output stores issued just before the barrier)
# baseline (speedup 1.0000x reference)
.LBB0_479:
	s_or_b64 exec, exec, s[4:5]
	s_add_i32 s4, s15, -8
	s_add_i32 s5, s15, 8
	s_cmp_lt_i32 s15, 2
	s_cselect_b64 s[90:91], -1, 0
	s_cmp_gt_i32 s15, 9
	s_cselect_b32 s20, s4, s15
	s_cmp_gt_i32 s15, 1
	s_cselect_b32 s21, s15, s5
	s_cmp_gt_i32 s21, 0
	s_cselect_b64 s[4:5], -1, 0
	s_cmp_gt_i32 s20, 0
	s_cselect_b64 s[18:19], -1, 0
	v_cndmask_b32_e64 v32, 0, 1, s[18:19]
	s_cmp_lt_i32 s20, 3
	v_readfirstlane_b32 s18, v32
	v_cndmask_b32_e64 v32, 0, 1, s[4:5]
	s_cselect_b32 s18, s18, 2
	s_cmp_lt_i32 s21, 3
	v_readfirstlane_b32 s4, v32
	s_cselect_b32 s4, s4, 2
	s_cmp_lt_i32 s21, 6
	s_cselect_b32 s22, s4, 3
	s_cmp_lt_i32 s20, 6
	s_cselect_b32 s18, s18, 3
	s_add_i32 s4, s18, 1
	s_mul_i32 s23, s4, s18
	s_lshr_b32 s4, s23, 1
	s_sub_i32 s20, s20, s4
	s_add_i32 s4, s22, 1
	s_mul_i32 s24, s4, s22
	s_lshr_b32 s4, s24, 1
	s_sub_i32 s25, s21, s4
	s_ashr_i32 s68, s16, 1
	s_and_b64 s[4:5], s[6:7], exec
	s_cselect_b32 s4, s92, 0x1b485000
	s_add_u32 s92, s78, s4
	s_addc_u32 s93, s79, 0
	s_cmp_gt_u32 s16, 1
	s_cselect_b64 s[94:95], -1, 0
	s_lshl_b32 s16, s68, 12
	s_add_i32 s69, 0, 0x15600
	s_add_i32 s4, s68, 1
	s_mul_i32 s71, s68, 0x480
	s_add_i32 s66, s69, s16
	s_mul_i32 s4, s71, s4
	s_addk_i32 s66, 0xff00
	s_lshl_b32 s30, s68, 8
	s_add_i32 s67, s4, 0
	s_cmp_lt_i32 s68, 3
	s_cselect_b64 s[96:97], -1, 0
	s_lshl_b32 s76, s2, 12
	s_sub_i32 s2, s44, s0
	s_lshl_b32 s0, s15, 6
	s_lshr_b32 s5, s17, 2
	s_and_b32 s0, s0, 0xc0
	s_and_b32 s4, s17, 3
	s_lshl_b32 s21, s5, 12
	v_readlane_b32 s39, v255, 10
	s_add_i32 s33, s0, 0
	v_lshl_or_b32 v39, s5, 4, v28
	s_add_i32 s5, s39, s21
	s_lshl_b32 s26, s4, 6
	s_bitset1_b32 s76, 11
	s_addk_i32 s2, 0x80
	s_add_i32 s0, s33, 0x19500
	s_lshl_b32 s17, s4, 5
	s_add_i32 s4, s26, s5
	s_cmp_lt_u32 s15, 12
	v_add_u32_e32 v40, s4, v29
	s_cselect_b64 s[50:51], -1, 0
	s_add_i32 s4, s15, 4
	s_lshr_b32 s4, s4, 2
	s_bfe_u32 s27, s1, 0x20006
	s_lshl_b32 s29, s4, 12
	v_lshl_or_b32 v41, s4, 4, v28
	s_add_i32 s4, s39, s29
	s_lshl_b32 s31, s27, 6
	s_lshl_b32 s28, s27, 5
	s_add_i32 s4, s31, s4
	s_cmp_lt_u32 s15, 6
	v_readlane_b32 s37, v255, 7
	v_mul_lo_u32 v41, v41, s61
	s_cselect_b64 s[56:57], -1, 0
	s_add_i32 s15, s15, 10
	v_mov_b32_e32 v37, s37
	v_add_u32_e32 v69, s58, v41
	v_add_u32_e32 v41, s4, v29
	s_and_b32 s4, s15, 3
	s_lshr_b32 s5, s15, 2
	v_mad_u32_u24 v37, v30, s61, v37
	s_lshl_b32 s15, s4, 5
	s_lshl_b32 s34, s5, 12
	v_add_u32_e32 v38, s17, v37
	v_add_u32_e32 v67, s28, v37
	v_add_u32_e32 v70, s15, v37
	v_lshl_or_b32 v37, s5, 4, v28
	s_add_i32 s5, s39, s34
	s_lshl_b32 s35, s4, 6
	v_mul_lo_u32 v37, v37, s61
	s_add_i32 s4, s35, s5
	v_add_u32_e32 v71, s58, v37
	v_add_u32_e32 v37, s4, v29
	s_and_b64 s[4:5], s[6:7], exec
	s_cselect_b32 s4, 1, -1
	s_ashr_i32 s1, s1, 8
	v_lshl_or_b32 v44, s1, 4, v28
	s_add_i32 s5, s1, 2
	v_mul_lo_u32 v45, v44, s61
	s_waitcnt lgkmcnt(0)
	v_exp_f32_e32 v32, v35
	v_and_b32_e32 v66, 0xff, v68
	v_add_u32_e32 v72, 0, v45
	v_lshl_or_b32 v45, s5, 4, v28
	s_add_i32 s62, s39, s16
	v_lshl_add_u32 v35, v66, 2, v36
	v_mul_u32_u24_e32 v36, 0x90, v30
	v_mad_u32_u24 v30, v30, s61, 0
	s_lshl_b32 s27, s27, 4
	v_mul_lo_u32 v46, v45, s61
	s_addk_i32 s62, 0xff00
	v_add_u32_e32 v42, s28, v30
	v_add_u32_e32 v73, 0, v46
	v_lshl_add_u32 v46, s1, 5, v30
	v_lshl_add_u32 v30, s5, 5, v30
	v_mul_lo_u32 v75, v44, s4
	v_mul_lo_u32 v77, v45, s4
	s_and_b64 s[4:5], s[6:7], exec
	s_cselect_b32 s1, 0xc0, 63
	ds_write_b32 v35, v32
	v_lshrrev_b32_e32 v32, 2, v68
	s_or_b32 s74, s1, s44
	s_add_i32 s1, s37, s17
	v_and_b32_e32 v32, 12, v32
	v_add_u32_e32 v44, s1, v65
	s_add_i32 s1, s69, s21
	v_or_b32_e32 v47, s27, v32
	s_add_i32 s26, s26, s1
	s_add_i32 s1, s37, s28
	v_lshlrev_b32_e32 v74, 1, v47
	v_or_b32_e32 v76, s14, v47
	v_add_u32_e32 v47, s1, v65
	s_add_i32 s1, s69, s29
	s_add_i32 s31, s31, s1
	s_add_i32 s1, s37, s15
	s_lshl_b32 s4, s20, 4
	v_add_u32_e32 v49, s1, v65
	s_add_i32 s1, s69, s34
	s_mulk_i32 s23, 0x480
	v_or_b32_e32 v50, s4, v28
	s_add_i32 s35, s35, s1
	s_add_i32 s1, s23, 0
	v_mul_lo_u32 v50, v50, s61
	v_sub_u32_e32 v35, v28, v32
	v_add_u32_e32 v50, s1, v50
	s_sub_i32 s1, s18, s20
	s_pack_ll_b32_b16 s19, s18, s22
	v_lshl_add_u32 v52, s1, 4, v35
	v_or_b32_e32 v53, s4, v32
	s_lshl_b32 s4, s25, 4
	v_or_b32_e32 v43, s27, v28
	v_pk_lshlrev_b16 v51, 4, s19 op_sel_hi:[0,1]
	v_cmp_lt_i32_e64 s[14:15], -1, v52
	v_cmp_lt_i32_e64 s[16:17], 0, v52
	v_cmp_lt_i32_e64 s[18:19], 1, v52
	v_cmp_lt_i32_e64 s[20:21], 2, v52
	v_lshlrev_b32_e32 v52, 1, v53
	s_mulk_i32 s24, 0x480
	v_or_b32_e32 v53, s4, v28
	v_perm_b32 v28, v28, v28, s36
	s_add_i32 s1, s24, 0
	v_mul_lo_u32 v53, v53, s61
	v_or_b32_e32 v28, v51, v28
	v_add_u32_e32 v53, s1, v53
	v_pk_mul_lo_u16 v28, v28, s61 op_sel_hi:[1,0]
	s_sub_i32 s1, s22, s25
	v_and_b32_e32 v51, 0xfff0, v28
	v_add_u32_sdwa v79, v181, v28 dst_sel:DWORD dst_unused:UNUSED_PAD src0_sel:DWORD src1_sel:WORD_1
	v_lshl_add_u32 v28, s1, 4, v35
	v_cmp_gt_i32_e32 vcc, 3, v31
	v_add_u32_e32 v45, s26, v29
	v_cmp_lt_i32_e64 s[22:23], -1, v28
	v_cmp_lt_i32_e64 s[24:25], 0, v28
	v_cmp_lt_i32_e64 s[26:27], 1, v28
	v_cmp_lt_i32_e64 s[28:29], 2, v28
	v_cndmask_b32_e64 v28, 3, 2, vcc
	v_cmp_lt_i32_e32 vcc, 0, v31
	s_add_i32 s45, s30, 0
	v_mul_lo_u32 v39, v39, s61
	v_cndmask_b32_e32 v28, 1, v28, vcc
	v_add_u32_e32 v35, -1, v28
	v_mul_i32_i24_e32 v35, v35, v28
	v_lshrrev_b32_e32 v35, 1, v35
	s_add_i32 s33, s33, 0x1d500
	v_add_u32_e32 v48, s31, v29
	v_or_b32_e32 v32, s4, v32
	s_add_i32 s77, s45, 0x22400
	s_add_i32 s45, s45, 0x22800
	v_cmp_ne_u32_e64 s[30:31], v31, v35
	v_sub_u32_e32 v31, v31, v35
	v_add_u32_e32 v80, s39, v34
	v_lshlrev_b32_e32 v28, 12, v28
	s_add_i32 s1, 0, 0x21e00
	v_add_u32_e32 v85, s69, v34
	v_add_u32_e32 v39, s58, v39
	v_mad_u32_u24 v43, v43, s61, 0
	v_add_u32_e32 v29, s35, v29
	v_add_u32_e32 v78, 0, v51
	v_lshlrev_b32_e32 v32, 1, v32
	v_lshlrev_b32_e32 v31, 12, v31
	v_add3_u32 v82, v80, v28, s38
	v_lshlrev_b32_e32 v33, 12, v33
	v_add3_u32 v87, v85, v28, s38
	s_add_u32 s58, s82, s48
	v_mov_b32_e32 v28, 0
	s_mov_b32 s47, 0
	v_add3_u32 v81, v80, v31, s38
	v_lshl_add_u32 v83, v68, 2, s1
	v_add3_u32 v84, v80, v33, s38
	v_add3_u32 v86, v85, v31, s38
	v_add3_u32 v88, v85, v33, s38
	s_addc_u32 s59, s83, 0
	s_addk_i32 s71, 0x480
	v_add_u32_e32 v89, v40, v64
	v_add_u32_e32 v90, v41, v64
	v_add_u32_e32 v91, v37, v64
	v_add_u32_e32 v92, v44, v36
	v_add_u32_e32 v93, v45, v64
	v_add_u32_e32 v94, v47, v36
	v_add_u32_e32 v95, v48, v64
	v_add_u32_e32 v96, v49, v36
	v_add_u32_e32 v97, v29, v64
	v_add_u32_e32 v98, v50, v64
	v_add_u32_e32 v99, v78, v52
	v_add_u32_e32 v100, v53, v64
	v_add_u32_e32 v101, v79, v32
	v_add_u32_e32 v102, v38, v65
	v_add_u32_e32 v103, v39, v64
	v_add_u32_e32 v104, v42, v65
	v_add_u32_e32 v105, v43, v64
	v_add_u32_e32 v106, v46, v65
	v_add_u32_e32 v107, v30, v65
	v_mov_b32_e32 v29, v28
	v_mov_b32_e32 v30, v28
	v_mov_b32_e32 v31, v28
	v_mov_b32_e32 v32, v28
	v_mov_b32_e32 v33, v28
	v_mov_b32_e32 v34, v28
	v_mov_b32_e32 v35, v28
	s_waitcnt lgkmcnt(0)
	s_barrier
	s_waitcnt vmcnt(0)
	s_branch .LBB0_481

.Lhg_skipB:
	s_waitcnt vmcnt(0)
	s_branch .LBB0_519
.LBB0_480:
	ds_read_b64_tr_b16 v[40:41], v104 offset:27648
	ds_read_b64_tr_b16 v[42:43], v104 offset:28224
	v_exp_f32_e32 v60, v36
	ds_read_b128 v[44:47], v109 offset:36864
	v_exp_f32_e32 v61, v37
	v_exp_f32_e32 v62, v38
	v_exp_f32_e32 v63, v39
	ds_read_b128 v[36:39], v108 offset:36864
	s_waitcnt lgkmcnt(1)
	v_mfma_f32_16x16x32_bf16 v[44:47], v[40:43], v[44:47], 0
	ds_read_b64_tr_b16 v[48:49], v104 offset:18432
	ds_read_b64_tr_b16 v[50:51], v104 offset:19008
	ds_read_b64_tr_b16 v[52:53], v104 offset:32256
	v_pk_mul_f32 v[34:35], v[34:35], v[62:63]
	v_pk_mul_f32 v[32:33], v[32:33], v[60:61]
	s_waitcnt lgkmcnt(3)
	v_mfma_f32_16x16x32_bf16 v[36:39], v[40:43], v[36:39], 0
	ds_read_b64_tr_b16 v[40:41], v106 offset:27648
	ds_read_b64_tr_b16 v[42:43], v106 offset:28224
	ds_read_b64_tr_b16 v[56:57], v107 offset:27648
	ds_read_b64_tr_b16 v[58:59], v107 offset:28224
	ds_read_b64_tr_b16 v[54:55], v104 offset:32832
	v_pk_mul_f32 v[30:31], v[30:31], v[62:63]
	v_pk_mul_f32 v[28:29], v[28:29], v[60:61]
	s_waitcnt lgkmcnt(3)
	v_mfma_f32_16x16x32_bf16 v[32:35], v[48:51], v[40:43], v[32:35]
	s_add_i32 s47, s47, 2
	s_and_b64 vcc, exec, s[60:61]
	s_mov_b32 s60, 0xffff0000
	s_waitcnt lgkmcnt(1)
	v_mfma_f32_16x16x32_bf16 v[40:43], v[48:51], v[56:59], v[28:31]
	s_nop 2
	ds_read_b128 v[28:31], v109 offset:36928
	ds_read_b64_tr_b16 v[48:49], v104 offset:23616
	ds_read_b128 v[56:59], v108 offset:36928
	s_movk_i32 s61, 0x90
	s_waitcnt lgkmcnt(2)
	v_mfma_f32_16x16x32_bf16 v[60:63], v[52:55], v[28:31], v[44:47]
	s_nop 2
	ds_read_b64_tr_b16 v[46:47], v104 offset:23040
	ds_read_b64_tr_b16 v[28:29], v106 offset:32256
	s_waitcnt lgkmcnt(2)
	v_mfma_f32_16x16x32_bf16 v[36:39], v[52:55], v[56:59], v[36:39]
	ds_read_b64_tr_b16 v[30:31], v106 offset:32832
	ds_read_b64_tr_b16 v[50:51], v107 offset:32256
	ds_read_b64_tr_b16 v[52:53], v107 offset:32832
	ds_read_b128 v[54:57], v105 offset:55296
	s_waitcnt lgkmcnt(3)
	v_mfma_f32_16x16x32_bf16 v[28:31], v[46:49], v[28:31], v[32:35]
	s_waitcnt lgkmcnt(1)
	v_mfma_f32_16x16x32_bf16 v[32:35], v[46:49], v[50:53], v[40:43]
	s_nop 2
	ds_read_b128 v[40:43], v109 offset:9216
	ds_read_b128 v[44:47], v108 offset:9216
	ds_read_b128 v[48:51], v105 offset:55360
	v_cvt_pk_bf16_f32 v52, v28, v29
	s_waitcnt lgkmcnt(1)
	v_mfma_f32_16x16x32_bf16 v[36:39], v[54:57], v[44:47], v[36:39]
	ds_read_b128 v[44:47], v109 offset:9280
	v_cvt_pk_bf16_f32 v53, v30, v31
	v_mfma_f32_16x16x32_bf16 v[40:43], v[54:57], v[40:43], v[60:63]
	s_waitcnt lgkmcnt(0)
	v_mfma_f32_16x16x32_bf16 v[40:43], v[48:51], v[44:47], v[40:43]
	ds_read_b128 v[44:47], v108 offset:9280
	ds_write_b64 v113, v[52:53] offset:46080
	s_waitcnt lgkmcnt(1)
	v_mfma_f32_16x16x32_bf16 v[36:39], v[48:51], v[44:47], v[36:39]
	v_cvt_pk_bf16_f32 v44, v32, v33
	v_cvt_pk_bf16_f32 v45, v34, v35
	ds_write_b64 v112, v[44:45] offset:46080
	v_add_u32_e32 v44, s34, v75
	v_lshl_or_b32 v180, v44, 10, v76
	v_cvt_pk_bf16_f32 v40, v40, v41
	v_cvt_pk_bf16_f32 v41, v42, v43
	v_lshl_add_u64 v[42:43], v[180:181], 1, s[92:93]
	global_store_dwordx2 v[42:43], v[40:41], off
	v_add_u32_e32 v40, s34, v77
	v_lshl_or_b32 v180, v40, 10, v76
	v_cvt_pk_bf16_f32 v36, v36, v37
	v_cvt_pk_bf16_f32 v37, v38, v39
	v_lshl_add_u64 v[38:39], v[180:181], 1, s[92:93]
	global_store_dwordx2 v[38:39], v[36:37], off
	s_waitcnt lgkmcnt(0)
	s_barrier
	s_cbranch_vccnz .LBB0_541
.LBB0_481:
	v_mov_b32_e32 v36, v68
	s_andn2_b64 vcc, exec, s[94:95]
	v_lshrrev_b32_e32 v37, 3, v36
	v_and_or_b32 v40, v37, 7, s70
	v_and_b32_e32 v41, 7, v36
	v_lshlrev_b32_e32 v36, 8, v40
	v_lshlrev_b32_e32 v37, 5, v41
	v_add3_u32 v36, s69, v36, v37
	ds_read_b128 v[44:47], v36
	ds_read_b128 v[36:39], v36 offset:16
	v_mul_lo_u32 v110, v40, s61
	v_lshlrev_b32_e32 v111, 4, v41
	v_cndmask_b32_e64 v40, 0, 1, s[94:95]
	v_lshlrev_b32_e32 v109, 3, v41
	v_add3_u32 v108, 0, v110, v111
	v_cmp_ne_u32_e64 s[34:35], 1, v40
	v_mov_b32_e32 v43, 0
	v_mov_b32_e32 v42, 0
	v_mov_b32_e32 v41, 0
	v_mov_b32_e32 v40, 0
	v_mov_b32_e32 v51, 0
	v_mov_b32_e32 v50, 0
	v_mov_b32_e32 v49, 0
	v_mov_b32_e32 v48, 0
	s_waitcnt vmcnt(7)
	ds_write_b128 v108, v[12:15] offset:27648
	s_cbranch_vccnz .LBB0_483
	v_lshl_add_u32 v40, v109, 2, s66
	ds_read_b128 v[48:51], v40
	ds_read_b128 v[40:43], v40 offset:16

.LBB0_488:
	v_mov_b32_e32 v36, v68
	s_cmpk_lt_u32 s47, 0x42
	v_lshrrev_b32_e32 v37, 3, v36
	v_and_or_b32 v37, v37, 7, s70
	v_lshlrev_b32_e32 v36, 4, v36
	s_cselect_b64 s[54:55], -1, 0
	s_cmpk_gt_u32 s47, 0x41
	v_mul_lo_u32 v37, v37, s61
	v_and_b32_e32 v36, 0x70, v36
	v_readlane_b32 s4, v255, 7
	s_cselect_b64 s[60:61], -1, 0
	s_movk_i32 s72, 0x90
	v_add3_u32 v36, s4, v37, v36
	s_and_b64 vcc, exec, s[60:61]
	s_waitcnt vmcnt(4)
	ds_write_b128 v36, v[20:23]
	s_waitcnt lgkmcnt(0)
	s_barrier
	s_cbranch_vccnz .Lhg_skipA
	s_lshl_b32 s4, s47, 6
	s_add_i32 s36, s4, 0xffffff80
	s_sub_i32 s37, 0x107f, s4
	v_mov_b32_e32 v4, v68
	s_and_b64 s[4:5], s[6:7], exec
	s_cselect_b32 s4, s36, s37
	v_lshrrev_b32_e32 v5, 3, v4
	s_add_i32 s4, s4, s76
	v_and_or_b32 v5, v5, 7, s70
	s_cmp_eq_u32 s47, 0
	v_sub_u32_e32 v6, 0, v5
	s_cselect_b32 s4, s2, s4
	v_cndmask_b32_e64 v5, v6, v5, s[6:7]
	v_add_u32_e32 v5, s4, v5
	v_mul_u32_u24_e32 v5, 0xe00, v5
	v_lshlrev_b32_e32 v4, 3, v4
	v_and_or_b32 v4, v4, 56, v5
	v_ashrrev_i32_e32 v5, 31, v4
	v_lshl_add_u64 v[12:13], v[4:5], 1, s[58:59]
	s_lshl_b32 s48, s73, 1
	v_lshl_add_u64 v[4:5], v[12:13], 0, s[48:49]
	global_load_dwordx4 v[4:7], v[4:5], off offset:1536
	s_nop 0
	global_load_dwordx4 v[8:11], v[12:13], off
	s_nop 0
	global_load_dwordx4 v[12:15], v[12:13], off offset:512

.LBB0_508:
	v_add_u32_e32 v109, v72, v64
	v_add_u32_e32 v108, v73, v64
	ds_read_b64_tr_b16 v[40:41], v104 offset:27648
	ds_read_b64_tr_b16 v[42:43], v104 offset:28224
	v_exp_f32_e32 v60, v36
	v_exp_f32_e32 v61, v37
	ds_read_b128 v[44:47], v109 offset:36864
	v_exp_f32_e32 v62, v38
	v_exp_f32_e32 v63, v39
	ds_read_b128 v[36:39], v108 offset:36864
	s_waitcnt lgkmcnt(1)
	v_mfma_f32_16x16x32_bf16 v[44:47], v[40:43], v[44:47], 0
	ds_read_b64_tr_b16 v[48:49], v104 offset:18432
	ds_read_b64_tr_b16 v[50:51], v104 offset:19008
	ds_read_b64_tr_b16 v[52:53], v104 offset:32256
	v_pk_mul_f32 v[30:31], v[30:31], v[62:63]
	v_pk_mul_f32 v[28:29], v[28:29], v[60:61]
	s_waitcnt lgkmcnt(3)
	v_mfma_f32_16x16x32_bf16 v[36:39], v[40:43], v[36:39], 0
	ds_read_b64_tr_b16 v[40:41], v106 offset:27648
	ds_read_b64_tr_b16 v[42:43], v106 offset:28224
	ds_read_b64_tr_b16 v[56:57], v107 offset:27648
	ds_read_b64_tr_b16 v[58:59], v107 offset:28224
	ds_read_b64_tr_b16 v[54:55], v104 offset:32832
	v_pk_mul_f32 v[34:35], v[34:35], v[62:63]
	v_pk_mul_f32 v[32:33], v[32:33], v[60:61]
	s_waitcnt lgkmcnt(3)
	v_mfma_f32_16x16x32_bf16 v[28:31], v[48:51], v[40:43], v[28:31]
	v_add_u32_e32 v113, v72, v74
	v_add_u32_e32 v112, v73, v74
	v_readlane_b32 s4, v255, 10
	s_waitcnt lgkmcnt(1)
	v_mfma_f32_16x16x32_bf16 v[40:43], v[48:51], v[56:59], v[32:35]
	s_nop 2
	ds_read_b128 v[32:35], v109 offset:36928
	ds_read_b64_tr_b16 v[48:49], v104 offset:23616
	ds_read_b128 v[56:59], v108 offset:36928
	s_and_b64 vcc, exec, s[34:35]
	s_waitcnt lgkmcnt(2)
	v_mfma_f32_16x16x32_bf16 v[60:63], v[52:55], v[32:35], v[44:47]
	s_nop 2
	ds_read_b64_tr_b16 v[46:47], v104 offset:23040
	ds_read_b64_tr_b16 v[32:33], v106 offset:32256
	s_waitcnt lgkmcnt(2)
	v_mfma_f32_16x16x32_bf16 v[36:39], v[52:55], v[56:59], v[36:39]
	ds_read_b64_tr_b16 v[34:35], v106 offset:32832
	ds_read_b64_tr_b16 v[50:51], v107 offset:32256
	ds_read_b64_tr_b16 v[52:53], v107 offset:32832
	ds_read_b128 v[54:57], v105 offset:46080
	s_waitcnt lgkmcnt(3)
	v_mfma_f32_16x16x32_bf16 v[32:35], v[46:49], v[32:35], v[28:31]
	s_waitcnt lgkmcnt(1)
	v_mfma_f32_16x16x32_bf16 v[28:31], v[46:49], v[50:53], v[40:43]
	s_nop 2
	ds_read_b128 v[40:43], v109 offset:9216
	ds_read_b128 v[44:47], v108 offset:9216
	ds_read_b128 v[48:51], v105 offset:46144
	s_waitcnt lgkmcnt(1)
	v_mfma_f32_16x16x32_bf16 v[36:39], v[54:57], v[44:47], v[36:39]
	ds_read_b128 v[44:47], v109 offset:9280
	v_mfma_f32_16x16x32_bf16 v[40:43], v[54:57], v[40:43], v[60:63]
	s_waitcnt lgkmcnt(0)
	v_mfma_f32_16x16x32_bf16 v[40:43], v[48:51], v[44:47], v[40:43]
	ds_read_b128 v[44:47], v108 offset:9280
	s_waitcnt lgkmcnt(0)
	v_mfma_f32_16x16x32_bf16 v[36:39], v[48:51], v[44:47], v[36:39]
	v_cvt_pk_bf16_f32 v44, v32, v33
	v_cvt_pk_bf16_f32 v45, v34, v35
	ds_write_b64 v113, v[44:45] offset:55296
	v_cvt_pk_bf16_f32 v44, v28, v29
	v_cvt_pk_bf16_f32 v45, v30, v31
	ds_write_b64 v112, v[44:45] offset:55296
	v_add_u32_e32 v44, s48, v75
	v_lshl_or_b32 v180, v44, 10, v76
	v_cvt_pk_bf16_f32 v40, v40, v41
	v_cvt_pk_bf16_f32 v41, v42, v43
	v_lshl_add_u64 v[42:43], v[180:181], 1, s[92:93]
	global_store_dwordx2 v[42:43], v[40:41], off
	v_add_u32_e32 v40, s48, v77
	v_lshl_or_b32 v180, v40, 10, v76
	v_cvt_pk_bf16_f32 v36, v36, v37
	v_cvt_pk_bf16_f32 v37, v38, v39
	v_lshl_add_u64 v[38:39], v[180:181], 1, s[92:93]
	global_store_dwordx2 v[38:39], v[36:37], off
	v_mov_b32_e32 v36, v68
	s_waitcnt lgkmcnt(0)
	s_barrier
	v_mov_b32_e32 v43, 0
	v_lshrrev_b32_e32 v37, 3, v36
	v_and_or_b32 v40, v37, 7, s70
	v_and_b32_e32 v41, 7, v36
	v_lshlrev_b32_e32 v36, 8, v40
	v_lshlrev_b32_e32 v37, 5, v41
	v_add3_u32 v36, s4, v36, v37
	ds_read_b128 v[44:47], v36
	ds_read_b128 v[36:39], v36 offset:16
	v_mul_lo_u32 v116, v40, s72
	v_lshlrev_b32_e32 v117, 4, v41
	v_lshlrev_b32_e32 v115, 3, v41
	v_add3_u32 v114, 0, v116, v117
	v_mov_b32_e32 v42, 0
	v_mov_b32_e32 v41, 0
	v_mov_b32_e32 v40, 0
	v_mov_b32_e32 v51, 0
	v_mov_b32_e32 v50, 0
	v_mov_b32_e32 v49, 0
	v_mov_b32_e32 v48, 0
	s_waitcnt vmcnt(7)
	ds_write_b128 v114, v[24:27] offset:27648
	s_cbranch_vccnz .LBB0_510
	v_lshl_add_u32 v40, v115, 2, s62
	ds_read_b128 v[48:51], v40
	ds_read_b128 v[40:43], v40 offset:16
